# first grid-wide wait uses the XCD-hierarchical barrier protocol (hand-written first call incl. census) instead of cg grid.sync
# speedup vs baseline: 1.0289x; 1.0157x over previous
.LBB0_61:
	s_waitcnt vmcnt(0) lgkmcnt(0)
	s_barrier
	s_mov_b64 s[0:1], exec
	v_readlane_b32 s2, v248, 3
	v_readlane_b32 s3, v248, 4
	s_and_b64 s[2:3], s[0:1], s[2:3]
	s_mov_b64 exec, s[2:3]
	s_cbranch_execz .LBB0_71
	v_readlane_b32 s4, v248, 1
	v_readlane_b32 s5, v248, 2
	v_mov_b32_e32 v0, 0
	v_mov_b32_e32 v21, 1
	v_mov_b32_e32 v20, s97
	v_lshlrev_b32_e32 v20, 8, v20
	s_mov_b32 s8, 0
	s_add_u32 s10, s4, 0x1000
	s_addc_u32 s11, s5, 0
.Lgs_census:
	global_load_dword v1, v0, s[4:5] offset:1024 sc1
	global_load_dword v2, v0, s[4:5] offset:1280 sc1
	global_load_dword v3, v0, s[4:5] offset:1536 sc1
	global_load_dword v4, v0, s[4:5] offset:1792 sc1
	global_load_dword v5, v0, s[4:5] offset:2048 sc1
	global_load_dword v6, v0, s[4:5] offset:2304 sc1
	global_load_dword v7, v0, s[4:5] offset:2560 sc1
	global_load_dword v8, v0, s[4:5] offset:2816 sc1
	global_load_dword v9, v0, s[4:5] offset:3072 sc1
	global_load_dword v10, v0, s[4:5] offset:3328 sc1
	global_load_dword v11, v0, s[4:5] offset:3584 sc1
	global_load_dword v12, v0, s[4:5] offset:3840 sc1
	global_load_dword v13, v0, s[10:11] sc1
	global_load_dword v14, v0, s[10:11] offset:256 sc1
	global_load_dword v15, v0, s[10:11] offset:512 sc1
	global_load_dword v16, v0, s[10:11] offset:768 sc1
	global_load_dword v19, v20, s[4:5] offset:1024 sc1
	s_waitcnt vmcnt(0)
	v_add_u32_e32 v17, v1, v2
	v_add3_u32 v17, v17, v3, v4
	v_add3_u32 v17, v17, v5, v6
	v_add3_u32 v17, v17, v7, v8
	v_add3_u32 v17, v17, v9, v10
	v_add3_u32 v17, v17, v11, v12
	v_add3_u32 v17, v17, v13, v14
	v_add3_u32 v17, v17, v15, v16
	s_nop 1
	v_readfirstlane_b32 s9, v17
	s_nop 3
	s_cmp_eq_u32 s9, s92
	s_cbranch_scc1 .Lgs_census_done
	s_sleep 1
	s_add_i32 s8, s8, 1
	s_cmp_lt_u32 s8, 0x40000
	s_cbranch_scc1 .Lgs_census
.Lgs_census_done:
	v_min_u32_e32 v18, 1, v1
	v_min_u32_e32 v22, 1, v2
	v_add_u32_e32 v18, v18, v22
	v_min_u32_e32 v22, 1, v3
	v_add_u32_e32 v18, v18, v22
	v_min_u32_e32 v22, 1, v4
	v_add_u32_e32 v18, v18, v22
	v_min_u32_e32 v22, 1, v5
	v_add_u32_e32 v18, v18, v22
	v_min_u32_e32 v22, 1, v6
	v_add_u32_e32 v18, v18, v22
	v_min_u32_e32 v22, 1, v7
	v_add_u32_e32 v18, v18, v22
	v_min_u32_e32 v22, 1, v8
	v_add_u32_e32 v18, v18, v22
	v_min_u32_e32 v22, 1, v9
	v_add_u32_e32 v18, v18, v22
	v_min_u32_e32 v22, 1, v10
	v_add_u32_e32 v18, v18, v22
	v_min_u32_e32 v22, 1, v11
	v_add_u32_e32 v18, v18, v22
	v_min_u32_e32 v22, 1, v12
	v_add_u32_e32 v18, v18, v22
	v_min_u32_e32 v22, 1, v13
	v_add_u32_e32 v18, v18, v22
	v_min_u32_e32 v22, 1, v14
	v_add_u32_e32 v18, v18, v22
	v_min_u32_e32 v22, 1, v15
	v_add_u32_e32 v18, v18, v22
	v_min_u32_e32 v22, 1, v16
	v_add_u32_e32 v18, v18, v22
	v_max_u32_e32 v19, 1, v19
	v_max_u32_e32 v18, 1, v18
	v_mov_b32_e32 v22, 0x20ff0
	ds_write_b32 v22, v19
	v_mov_b32_e32 v22, 0x20ff4
	ds_write_b32 v22, v18
	global_atomic_add v3, v20, v21, s[10:11] offset:1024 sc0
	s_waitcnt vmcnt(0) lgkmcnt(0)
	v_add_u32_e32 v3, 1, v3
	v_cmp_ne_u32_e32 vcc, v3, v19
	s_cbranch_vccnz .Lgs_follower
	buffer_wbl2 sc1
	s_waitcnt vmcnt(0)
	v_mov_b32_e32 v5, 0x2400
	global_atomic_add v6, v5, v21, s[10:11] sc0
	s_waitcnt vmcnt(0)
	v_add_u32_e32 v6, 1, v6
	v_cmp_ne_u32_e32 vcc, v6, v18
	v_mov_b32_e32 v5, 0x2500
	s_cbranch_vccnz .Lgs_top_wait
	global_atomic_add v5, v21, s[10:11]
	s_branch .Lgs_top_done
.Lgs_top_wait:
	s_mov_b32 s8, 0
.Lgs_top_spin:
	s_sleep 1
	global_load_dword v7, v5, s[10:11] sc1
	s_waitcnt vmcnt(0)
	v_cmp_ne_u32_e32 vcc, 0, v7
	s_cbranch_vccnz .Lgs_top_done
	s_add_i32 s8, s8, 1
	s_cmp_lt_u32 s8, 0x40000
	s_cbranch_scc1 .Lgs_top_spin
.Lgs_top_done:
	s_waitcnt vmcnt(0)
	buffer_inv sc1
	v_add_u32_e32 v5, 0x1400, v20
	global_atomic_add v5, v21, s[10:11]
	s_waitcnt vmcnt(0)
	s_branch .LBB0_71
.Lgs_follower:
	v_add_u32_e32 v5, 0x1400, v20
	s_mov_b32 s8, 0

.Lgs_f_done:
	buffer_inv sc1
	s_waitcnt vmcnt(0)
